# gate-up epilogue: scale and 1+e steps as packed f32 ops
# speedup vs baseline: 1.0388x; 1.0037x over previous
; __device__ __forceinline__ unsigned cvt_pk_bf16(float lo, float hi) { unsigned r; asm volatile("v_cvt_pk_bf16_f32 %0, %1, %2" : "=v"(r) : "v"(lo), "v"(hi)); return r; }
; __device__ __forceinline__ float rstd_of(float ss) { return __builtin_amdgcn_rsqf(ss * (1.0f / 1024.0f) + RMS_EPS_F); }
; __device__ __forceinline__ float silu_mul(float g, float u) { return g * __builtin_amdgcn_rcpf(1.0f + __builtin_amdgcn_exp2f(-1.4426950408889634f * g)) * u; }
;     __device__ __forceinline__ void operator()(const f32x4 (&acc)[2][2][4][2], const Unit& u, int wr, int wc, int fr_in, int fq_in) const {
;     ...
;             for (int m = 0; m < 4; ++m) { const int row = row0 + ai * HALF + m * 16; const float rs = rstd_of(ssq[ai][m]);
;                 const f32x4 g0 = acc[ai][0][m][0] * rs, g1 = acc[ai][0][m][1] * rs, u0 = acc[ai][1][m][0] * rs, u1 = acc[ai][1][m][1] * rs;
;                 u32x4 w; w.x = cvt_pk_bf16(silu_mul(g0[0], u0[0]), silu_mul(g0[1], u0[1])); w.y = cvt_pk_bf16(silu_mul(g0[2], u0[2]), silu_mul(g0[3], u0[3]));
;                 w.z = cvt_pk_bf16(silu_mul(g1[0], u1[0]), silu_mul(g1[1], u1[1])); w.w = cvt_pk_bf16(silu_mul(g1[2], u1[2]), silu_mul(g1[3], u1[3]));
;                 *(u32x4*)(act + (size_t)row * 4096 + col0) = w; }
.LBB0_645:
	s_lshl_b32 s26, s50, 8
	s_add_i32 s26, s26, s64
	s_lshl_b32 s22, s22, 7
	v_add_u32_e32 v142, s26, v144
	s_or_b32 s22, s22, s65
	v_lshl_add_u32 v140, v145, 3, s22
	v_lshlrev_b32_e32 v172, 13, v142
	s_mov_b64 s[50:51], -1
	v_lshl_add_u32 v172, v140, 1, v172
	v_fmamk_f32 v170, v220, 0x3a800000, v213
	v_rsq_f32_e32 v171, v170
	v_mov_b32_e32 v174, v172
	v_mul_f32_e32 v168, 0xbfb8aa3b, v171
	v_pk_mul_f32 v[160:161], v[128:129], v[168:169] op_sel_hi:[1,0]
	v_pk_mul_f32 v[162:163], v[130:131], v[168:169] op_sel_hi:[1,0]
	v_pk_mul_f32 v[164:165], v[124:125], v[168:169] op_sel_hi:[1,0]
	v_pk_mul_f32 v[166:167], v[126:127], v[168:169] op_sel_hi:[1,0]
	v_exp_f32_e32 v160, v160
	v_exp_f32_e32 v161, v161
	v_exp_f32_e32 v162, v162
	v_exp_f32_e32 v163, v163
	v_exp_f32_e32 v164, v164
	v_exp_f32_e32 v165, v165
	v_exp_f32_e32 v166, v166
	v_exp_f32_e32 v167, v167
	v_pk_fma_f32 v[160:161], v[160:161], v[170:171], v[170:171] op_sel_hi:[1,0,0]
	v_pk_fma_f32 v[162:163], v[162:163], v[170:171], v[170:171] op_sel_hi:[1,0,0]
	v_pk_fma_f32 v[164:165], v[164:165], v[170:171], v[170:171] op_sel_hi:[1,0,0]
	v_pk_fma_f32 v[166:167], v[166:167], v[170:171], v[170:171] op_sel_hi:[1,0,0]
	v_rcp_f32_e32 v160, v160
	v_rcp_f32_e32 v161, v161
	v_rcp_f32_e32 v162, v162
	v_rcp_f32_e32 v163, v163
	v_rcp_f32_e32 v164, v164
	v_rcp_f32_e32 v165, v165
	v_rcp_f32_e32 v166, v166
	v_rcp_f32_e32 v167, v167
	v_pk_mul_f32 v[128:129], v[128:129], v[120:121]
	v_pk_mul_f32 v[130:131], v[130:131], v[122:123]
	v_pk_mul_f32 v[124:125], v[124:125], v[116:117]
	v_pk_mul_f32 v[126:127], v[126:127], v[118:119]
	v_pk_mul_f32 v[128:129], v[128:129], v[160:161]
	v_pk_mul_f32 v[130:131], v[130:131], v[162:163]
	v_pk_mul_f32 v[124:125], v[124:125], v[164:165]
	v_pk_mul_f32 v[126:127], v[126:127], v[166:167]
	v_cvt_pk_bf16_f32 v120, v128, v129
	v_cvt_pk_bf16_f32 v121, v130, v131
	v_cvt_pk_bf16_f32 v122, v124, v125
	v_cvt_pk_bf16_f32 v123, v126, v127
	global_store_dwordx4 v174, v[120:123], s[92:93]
	v_fmamk_f32 v170, v221, 0x3a800000, v213
	v_rsq_f32_e32 v171, v170
	v_add_u32_e32 v174, 0x20000, v172
	v_mul_f32_e32 v168, 0xbfb8aa3b, v171
	v_pk_mul_f32 v[160:161], v[112:113], v[168:169] op_sel_hi:[1,0]
	v_pk_mul_f32 v[162:163], v[114:115], v[168:169] op_sel_hi:[1,0]
	v_pk_mul_f32 v[164:165], v[108:109], v[168:169] op_sel_hi:[1,0]
	v_pk_mul_f32 v[166:167], v[110:111], v[168:169] op_sel_hi:[1,0]
	v_exp_f32_e32 v160, v160
	v_exp_f32_e32 v161, v161
	v_exp_f32_e32 v162, v162
	v_exp_f32_e32 v163, v163
	v_exp_f32_e32 v164, v164
	v_exp_f32_e32 v165, v165
	v_exp_f32_e32 v166, v166
	v_exp_f32_e32 v167, v167
	v_pk_fma_f32 v[160:161], v[160:161], v[170:171], v[170:171] op_sel_hi:[1,0,0]
	v_pk_fma_f32 v[162:163], v[162:163], v[170:171], v[170:171] op_sel_hi:[1,0,0]
	v_pk_fma_f32 v[164:165], v[164:165], v[170:171], v[170:171] op_sel_hi:[1,0,0]
	v_pk_fma_f32 v[166:167], v[166:167], v[170:171], v[170:171] op_sel_hi:[1,0,0]
	v_rcp_f32_e32 v160, v160
	v_rcp_f32_e32 v161, v161
	v_rcp_f32_e32 v162, v162
	v_rcp_f32_e32 v163, v163
	v_rcp_f32_e32 v164, v164
	v_rcp_f32_e32 v165, v165
	v_rcp_f32_e32 v166, v166
	v_rcp_f32_e32 v167, v167
	v_pk_mul_f32 v[112:113], v[112:113], v[104:105]
	v_pk_mul_f32 v[114:115], v[114:115], v[106:107]
	v_pk_mul_f32 v[108:109], v[108:109], v[100:101]
	v_pk_mul_f32 v[110:111], v[110:111], v[102:103]
	v_pk_mul_f32 v[112:113], v[112:113], v[160:161]
	v_pk_mul_f32 v[114:115], v[114:115], v[162:163]
	v_pk_mul_f32 v[108:109], v[108:109], v[164:165]
	v_pk_mul_f32 v[110:111], v[110:111], v[166:167]
	v_cvt_pk_bf16_f32 v104, v112, v113
	v_cvt_pk_bf16_f32 v105, v114, v115
	v_cvt_pk_bf16_f32 v106, v108, v109
	v_cvt_pk_bf16_f32 v107, v110, v111
	global_store_dwordx4 v174, v[104:107], s[92:93]
	v_fmamk_f32 v170, v248, 0x3a800000, v213
	v_rsq_f32_e32 v171, v170
	v_add_u32_e32 v174, 0x40000, v172
	v_mul_f32_e32 v168, 0xbfb8aa3b, v171
	v_pk_mul_f32 v[160:161], v[96:97], v[168:169] op_sel_hi:[1,0]
	v_pk_mul_f32 v[162:163], v[98:99], v[168:169] op_sel_hi:[1,0]
	v_pk_mul_f32 v[164:165], v[92:93], v[168:169] op_sel_hi:[1,0]
	v_pk_mul_f32 v[166:167], v[94:95], v[168:169] op_sel_hi:[1,0]
	v_exp_f32_e32 v160, v160
	v_exp_f32_e32 v161, v161
	v_exp_f32_e32 v162, v162
	v_exp_f32_e32 v163, v163
	v_exp_f32_e32 v164, v164
	v_exp_f32_e32 v165, v165
	v_exp_f32_e32 v166, v166
	v_exp_f32_e32 v167, v167
	v_pk_fma_f32 v[160:161], v[160:161], v[170:171], v[170:171] op_sel_hi:[1,0,0]
	v_pk_fma_f32 v[162:163], v[162:163], v[170:171], v[170:171] op_sel_hi:[1,0,0]
	v_pk_fma_f32 v[164:165], v[164:165], v[170:171], v[170:171] op_sel_hi:[1,0,0]
	v_pk_fma_f32 v[166:167], v[166:167], v[170:171], v[170:171] op_sel_hi:[1,0,0]
	v_rcp_f32_e32 v160, v160
	v_rcp_f32_e32 v161, v161
	v_rcp_f32_e32 v162, v162
	v_rcp_f32_e32 v163, v163
	v_rcp_f32_e32 v164, v164
	v_rcp_f32_e32 v165, v165
	v_rcp_f32_e32 v166, v166
	v_rcp_f32_e32 v167, v167
	v_pk_mul_f32 v[96:97], v[96:97], v[88:89]
	v_pk_mul_f32 v[98:99], v[98:99], v[90:91]
	v_pk_mul_f32 v[92:93], v[92:93], v[84:85]
	v_pk_mul_f32 v[94:95], v[94:95], v[86:87]
	v_pk_mul_f32 v[96:97], v[96:97], v[160:161]
	v_pk_mul_f32 v[98:99], v[98:99], v[162:163]
	v_pk_mul_f32 v[92:93], v[92:93], v[164:165]
	v_pk_mul_f32 v[94:95], v[94:95], v[166:167]
	v_cvt_pk_bf16_f32 v88, v96, v97
	v_cvt_pk_bf16_f32 v89, v98, v99
	v_cvt_pk_bf16_f32 v90, v92, v93
	v_cvt_pk_bf16_f32 v91, v94, v95
	global_store_dwordx4 v174, v[88:91], s[92:93]
	v_fmamk_f32 v170, v249, 0x3a800000, v213
	v_rsq_f32_e32 v171, v170
	v_add_u32_e32 v174, 0x60000, v172
	v_mul_f32_e32 v168, 0xbfb8aa3b, v171
	v_pk_mul_f32 v[160:161], v[80:81], v[168:169] op_sel_hi:[1,0]
	v_pk_mul_f32 v[162:163], v[82:83], v[168:169] op_sel_hi:[1,0]
; __device__ __forceinline__ unsigned cvt_pk_bf16(float lo, float hi) { unsigned r; asm volatile("v_cvt_pk_bf16_f32 %0, %1, %2" : "=v"(r) : "v"(lo), "v"(hi)); return r; }
; __device__ __forceinline__ float rstd_of(float ss) { return __builtin_amdgcn_rsqf(ss * (1.0f / 1024.0f) + RMS_EPS_F); }
; __device__ __forceinline__ float silu_mul(float g, float u) { return g * __builtin_amdgcn_rcpf(1.0f + __builtin_amdgcn_exp2f(-1.4426950408889634f * g)) * u; }
;     __device__ __forceinline__ void operator()(const f32x4 (&acc)[2][2][4][2], const Unit& u, int wr, int wc, int fr_in, int fq_in) const {
;     ...
;             for (int m = 0; m < 4; ++m) { const int row = row0 + ai * HALF + m * 16; const float rs = rstd_of(ssq[ai][m]);
;                 const f32x4 g0 = acc[ai][0][m][0] * rs, g1 = acc[ai][0][m][1] * rs, u0 = acc[ai][1][m][0] * rs, u1 = acc[ai][1][m][1] * rs;
;                 u32x4 w; w.x = cvt_pk_bf16(silu_mul(g0[0], u0[0]), silu_mul(g0[1], u0[1])); w.y = cvt_pk_bf16(silu_mul(g0[2], u0[2]), silu_mul(g0[3], u0[3]));
;                 w.z = cvt_pk_bf16(silu_mul(g1[0], u1[0]), silu_mul(g1[1], u1[1])); w.w = cvt_pk_bf16(silu_mul(g1[2], u1[2]), silu_mul(g1[3], u1[3]));
;                 *(u32x4*)(act + (size_t)row * 4096 + col0) = w; }
	v_pk_mul_f32 v[164:165], v[76:77], v[168:169] op_sel_hi:[1,0]
	v_pk_mul_f32 v[166:167], v[78:79], v[168:169] op_sel_hi:[1,0]
	v_exp_f32_e32 v160, v160
	v_exp_f32_e32 v161, v161
	v_exp_f32_e32 v162, v162
	v_exp_f32_e32 v163, v163
	v_exp_f32_e32 v164, v164
	v_exp_f32_e32 v165, v165
	v_exp_f32_e32 v166, v166
	v_exp_f32_e32 v167, v167
	v_pk_fma_f32 v[160:161], v[160:161], v[170:171], v[170:171] op_sel_hi:[1,0,0]
	v_pk_fma_f32 v[162:163], v[162:163], v[170:171], v[170:171] op_sel_hi:[1,0,0]
	v_pk_fma_f32 v[164:165], v[164:165], v[170:171], v[170:171] op_sel_hi:[1,0,0]
	v_pk_fma_f32 v[166:167], v[166:167], v[170:171], v[170:171] op_sel_hi:[1,0,0]
	v_rcp_f32_e32 v160, v160
	v_rcp_f32_e32 v161, v161
	v_rcp_f32_e32 v162, v162
	v_rcp_f32_e32 v163, v163
	v_rcp_f32_e32 v164, v164
	v_rcp_f32_e32 v165, v165
	v_rcp_f32_e32 v166, v166
	v_rcp_f32_e32 v167, v167
	v_pk_mul_f32 v[80:81], v[80:81], v[72:73]
	v_pk_mul_f32 v[82:83], v[82:83], v[74:75]
	v_pk_mul_f32 v[76:77], v[76:77], v[68:69]
	v_pk_mul_f32 v[78:79], v[78:79], v[70:71]
	v_pk_mul_f32 v[80:81], v[80:81], v[160:161]
	v_pk_mul_f32 v[82:83], v[82:83], v[162:163]
	v_pk_mul_f32 v[76:77], v[76:77], v[164:165]
	v_pk_mul_f32 v[78:79], v[78:79], v[166:167]
	v_cvt_pk_bf16_f32 v72, v80, v81
	v_cvt_pk_bf16_f32 v73, v82, v83
	v_cvt_pk_bf16_f32 v74, v76, v77
	v_cvt_pk_bf16_f32 v75, v78, v79
	global_store_dwordx4 v174, v[72:75], s[92:93]
	v_fmamk_f32 v170, v250, 0x3a800000, v213
	v_rsq_f32_e32 v171, v170
	v_add_u32_e32 v174, 0x100000, v172
	v_mul_f32_e32 v168, 0xbfb8aa3b, v171
	v_pk_mul_f32 v[160:161], v[64:65], v[168:169] op_sel_hi:[1,0]
	v_pk_mul_f32 v[162:163], v[66:67], v[168:169] op_sel_hi:[1,0]
	v_pk_mul_f32 v[164:165], v[60:61], v[168:169] op_sel_hi:[1,0]
	v_pk_mul_f32 v[166:167], v[62:63], v[168:169] op_sel_hi:[1,0]
	v_exp_f32_e32 v160, v160
	v_exp_f32_e32 v161, v161
	v_exp_f32_e32 v162, v162
	v_exp_f32_e32 v163, v163
	v_exp_f32_e32 v164, v164
	v_exp_f32_e32 v165, v165
	v_exp_f32_e32 v166, v166
	v_exp_f32_e32 v167, v167
	v_pk_fma_f32 v[160:161], v[160:161], v[170:171], v[170:171] op_sel_hi:[1,0,0]
	v_pk_fma_f32 v[162:163], v[162:163], v[170:171], v[170:171] op_sel_hi:[1,0,0]
	v_pk_fma_f32 v[164:165], v[164:165], v[170:171], v[170:171] op_sel_hi:[1,0,0]
	v_pk_fma_f32 v[166:167], v[166:167], v[170:171], v[170:171] op_sel_hi:[1,0,0]
	v_rcp_f32_e32 v160, v160
	v_rcp_f32_e32 v161, v161
	v_rcp_f32_e32 v162, v162
	v_rcp_f32_e32 v163, v163
	v_rcp_f32_e32 v164, v164
	v_rcp_f32_e32 v165, v165
	v_rcp_f32_e32 v166, v166
	v_rcp_f32_e32 v167, v167
	v_pk_mul_f32 v[64:65], v[64:65], v[56:57]
	v_pk_mul_f32 v[66:67], v[66:67], v[58:59]
	v_pk_mul_f32 v[60:61], v[60:61], v[52:53]
	v_pk_mul_f32 v[62:63], v[62:63], v[54:55]
	v_pk_mul_f32 v[64:65], v[64:65], v[160:161]
	v_pk_mul_f32 v[66:67], v[66:67], v[162:163]
	v_pk_mul_f32 v[60:61], v[60:61], v[164:165]
	v_pk_mul_f32 v[62:63], v[62:63], v[166:167]
	v_cvt_pk_bf16_f32 v56, v64, v65
	v_cvt_pk_bf16_f32 v57, v66, v67
	v_cvt_pk_bf16_f32 v58, v60, v61
	v_cvt_pk_bf16_f32 v59, v62, v63
	global_store_dwordx4 v174, v[56:59], s[92:93]
	v_fmamk_f32 v170, v251, 0x3a800000, v213
	v_rsq_f32_e32 v171, v170
	v_add_u32_e32 v174, 0x120000, v172
	v_mul_f32_e32 v168, 0xbfb8aa3b, v171
	v_pk_mul_f32 v[160:161], v[48:49], v[168:169] op_sel_hi:[1,0]
	v_pk_mul_f32 v[162:163], v[50:51], v[168:169] op_sel_hi:[1,0]
	v_pk_mul_f32 v[164:165], v[44:45], v[168:169] op_sel_hi:[1,0]
	v_pk_mul_f32 v[166:167], v[46:47], v[168:169] op_sel_hi:[1,0]
	v_exp_f32_e32 v160, v160
	v_exp_f32_e32 v161, v161
	v_exp_f32_e32 v162, v162
	v_exp_f32_e32 v163, v163
	v_exp_f32_e32 v164, v164
	v_exp_f32_e32 v165, v165
	v_exp_f32_e32 v166, v166
	v_exp_f32_e32 v167, v167
	v_pk_fma_f32 v[160:161], v[160:161], v[170:171], v[170:171] op_sel_hi:[1,0,0]
	v_pk_fma_f32 v[162:163], v[162:163], v[170:171], v[170:171] op_sel_hi:[1,0,0]
	v_pk_fma_f32 v[164:165], v[164:165], v[170:171], v[170:171] op_sel_hi:[1,0,0]
	v_pk_fma_f32 v[166:167], v[166:167], v[170:171], v[170:171] op_sel_hi:[1,0,0]
	v_rcp_f32_e32 v160, v160
	v_rcp_f32_e32 v161, v161
	v_rcp_f32_e32 v162, v162
	v_rcp_f32_e32 v163, v163
; __device__ __forceinline__ unsigned cvt_pk_bf16(float lo, float hi) { unsigned r; asm volatile("v_cvt_pk_bf16_f32 %0, %1, %2" : "=v"(r) : "v"(lo), "v"(hi)); return r; }
; __device__ __forceinline__ float rstd_of(float ss) { return __builtin_amdgcn_rsqf(ss * (1.0f / 1024.0f) + RMS_EPS_F); }
; __device__ __forceinline__ float silu_mul(float g, float u) { return g * __builtin_amdgcn_rcpf(1.0f + __builtin_amdgcn_exp2f(-1.4426950408889634f * g)) * u; }
; #define PG8_BAR __builtin_amdgcn_s_barrier()
;     __device__ __forceinline__ void operator()(const f32x4 (&acc)[2][2][4][2], const Unit& u, int wr, int wc, int fr_in, int fq_in) const {
;     ...
;             for (int m = 0; m < 4; ++m) { const int row = row0 + ai * HALF + m * 16; const float rs = rstd_of(ssq[ai][m]);
;                 const f32x4 g0 = acc[ai][0][m][0] * rs, g1 = acc[ai][0][m][1] * rs, u0 = acc[ai][1][m][0] * rs, u1 = acc[ai][1][m][1] * rs;
;                 u32x4 w; w.x = cvt_pk_bf16(silu_mul(g0[0], u0[0]), silu_mul(g0[1], u0[1])); w.y = cvt_pk_bf16(silu_mul(g0[2], u0[2]), silu_mul(g0[3], u0[3]));
;                 w.z = cvt_pk_bf16(silu_mul(g1[0], u1[0]), silu_mul(g1[1], u1[1])); w.w = cvt_pk_bf16(silu_mul(g1[2], u1[2]), silu_mul(g1[3], u1[3]));
;                 *(u32x4*)(act + (size_t)row * 4096 + col0) = w; }
; template <class Epi, class Sched, bool ALIGN_EPI = false, bool SP2 = false>
; __device__ __forceinline__ void gemm_phase(PG8_LAS unsigned char* lds, const Gemm g, const Sched& S, const Epi& E) {
;     ...
;         if (!has_next) break;
; #pragma unroll
;         for (int a = 0; a < 2; ++a)
; #pragma unroll
;             for (int b = 0; b < 2; ++b)
; #pragma unroll
;                 for (int m = 0; m < 4; ++m)
; #pragma unroll
;                     for (int n = 0; n < 2; ++n) acc[a][b][m][n] = (f32x4){0.f, 0.f, 0.f, 0.f};
;         cur = nxt; cA = nA; cB = nB; ++ui;
;         if constexpr (ALIGN_EPI) { if (wr == 1) PG8_BAR; }
	v_rcp_f32_e32 v164, v164
	v_rcp_f32_e32 v165, v165
	v_rcp_f32_e32 v166, v166
	v_rcp_f32_e32 v167, v167
	v_pk_mul_f32 v[48:49], v[48:49], v[40:41]
	v_pk_mul_f32 v[50:51], v[50:51], v[42:43]
	v_pk_mul_f32 v[44:45], v[44:45], v[36:37]
	v_pk_mul_f32 v[46:47], v[46:47], v[38:39]
	v_pk_mul_f32 v[48:49], v[48:49], v[160:161]
	v_pk_mul_f32 v[50:51], v[50:51], v[162:163]
	v_pk_mul_f32 v[44:45], v[44:45], v[164:165]
	v_pk_mul_f32 v[46:47], v[46:47], v[166:167]
	v_cvt_pk_bf16_f32 v40, v48, v49
	v_cvt_pk_bf16_f32 v41, v50, v51
	v_cvt_pk_bf16_f32 v42, v44, v45
	v_cvt_pk_bf16_f32 v43, v46, v47
	global_store_dwordx4 v174, v[40:43], s[92:93]
	v_fmamk_f32 v170, v252, 0x3a800000, v213
	v_rsq_f32_e32 v171, v170
	v_add_u32_e32 v174, 0x140000, v172
	v_mul_f32_e32 v168, 0xbfb8aa3b, v171
	v_pk_mul_f32 v[160:161], v[32:33], v[168:169] op_sel_hi:[1,0]
	v_pk_mul_f32 v[162:163], v[34:35], v[168:169] op_sel_hi:[1,0]
	v_pk_mul_f32 v[164:165], v[28:29], v[168:169] op_sel_hi:[1,0]
	v_pk_mul_f32 v[166:167], v[30:31], v[168:169] op_sel_hi:[1,0]
	v_exp_f32_e32 v160, v160
	v_exp_f32_e32 v161, v161
	v_exp_f32_e32 v162, v162
	v_exp_f32_e32 v163, v163
	v_exp_f32_e32 v164, v164
	v_exp_f32_e32 v165, v165
	v_exp_f32_e32 v166, v166
	v_exp_f32_e32 v167, v167
	v_pk_fma_f32 v[160:161], v[160:161], v[170:171], v[170:171] op_sel_hi:[1,0,0]
	v_pk_fma_f32 v[162:163], v[162:163], v[170:171], v[170:171] op_sel_hi:[1,0,0]
	v_pk_fma_f32 v[164:165], v[164:165], v[170:171], v[170:171] op_sel_hi:[1,0,0]
	v_pk_fma_f32 v[166:167], v[166:167], v[170:171], v[170:171] op_sel_hi:[1,0,0]
	v_rcp_f32_e32 v160, v160
	v_rcp_f32_e32 v161, v161
	v_rcp_f32_e32 v162, v162
	v_rcp_f32_e32 v163, v163
	v_rcp_f32_e32 v164, v164
	v_rcp_f32_e32 v165, v165
	v_rcp_f32_e32 v166, v166
	v_rcp_f32_e32 v167, v167
	v_pk_mul_f32 v[32:33], v[32:33], v[24:25]
	v_pk_mul_f32 v[34:35], v[34:35], v[26:27]
	v_pk_mul_f32 v[28:29], v[28:29], v[20:21]
	v_pk_mul_f32 v[30:31], v[30:31], v[22:23]
	v_pk_mul_f32 v[32:33], v[32:33], v[160:161]
	v_pk_mul_f32 v[34:35], v[34:35], v[162:163]
	v_pk_mul_f32 v[28:29], v[28:29], v[164:165]
	v_pk_mul_f32 v[30:31], v[30:31], v[166:167]
	v_cvt_pk_bf16_f32 v24, v32, v33
	v_cvt_pk_bf16_f32 v25, v34, v35
	v_cvt_pk_bf16_f32 v26, v28, v29
	v_cvt_pk_bf16_f32 v27, v30, v31
	global_store_dwordx4 v174, v[24:27], s[92:93]
	v_fmamk_f32 v170, v253, 0x3a800000, v213
	v_rsq_f32_e32 v171, v170
	v_add_u32_e32 v174, 0x160000, v172
	v_mul_f32_e32 v168, 0xbfb8aa3b, v171
	v_pk_mul_f32 v[160:161], v[16:17], v[168:169] op_sel_hi:[1,0]
	v_pk_mul_f32 v[162:163], v[18:19], v[168:169] op_sel_hi:[1,0]
	v_pk_mul_f32 v[164:165], v[12:13], v[168:169] op_sel_hi:[1,0]
	v_pk_mul_f32 v[166:167], v[14:15], v[168:169] op_sel_hi:[1,0]
	v_exp_f32_e32 v160, v160
	v_exp_f32_e32 v161, v161
	v_exp_f32_e32 v162, v162
	v_exp_f32_e32 v163, v163
	v_exp_f32_e32 v164, v164
	v_exp_f32_e32 v165, v165
	v_exp_f32_e32 v166, v166
	v_exp_f32_e32 v167, v167
	v_pk_fma_f32 v[160:161], v[160:161], v[170:171], v[170:171] op_sel_hi:[1,0,0]
	v_pk_fma_f32 v[162:163], v[162:163], v[170:171], v[170:171] op_sel_hi:[1,0,0]
	v_pk_fma_f32 v[164:165], v[164:165], v[170:171], v[170:171] op_sel_hi:[1,0,0]
	v_pk_fma_f32 v[166:167], v[166:167], v[170:171], v[170:171] op_sel_hi:[1,0,0]
	v_rcp_f32_e32 v160, v160
	v_rcp_f32_e32 v161, v161
	v_rcp_f32_e32 v162, v162
	v_rcp_f32_e32 v163, v163
	v_rcp_f32_e32 v164, v164
	v_rcp_f32_e32 v165, v165
	v_rcp_f32_e32 v166, v166
	v_rcp_f32_e32 v167, v167
	v_pk_mul_f32 v[16:17], v[16:17], v[8:9]
	v_pk_mul_f32 v[18:19], v[18:19], v[10:11]
	v_pk_mul_f32 v[12:13], v[12:13], v[4:5]
	v_pk_mul_f32 v[14:15], v[14:15], v[6:7]
	v_pk_mul_f32 v[16:17], v[16:17], v[160:161]
	v_pk_mul_f32 v[18:19], v[18:19], v[162:163]
	v_pk_mul_f32 v[12:13], v[12:13], v[164:165]
	v_pk_mul_f32 v[14:15], v[14:15], v[166:167]
	v_cvt_pk_bf16_f32 v8, v16, v17
	v_cvt_pk_bf16_f32 v9, v18, v19
	v_cvt_pk_bf16_f32 v10, v12, v13
	v_cvt_pk_bf16_f32 v11, v14, v15
	global_store_dwordx4 v174, v[8:11], s[92:93]
	s_andn2_b64 vcc, exec, s[40:41]
	s_cbranch_vccnz .LBB0_634
	s_andn2_b64 vcc, exec, s[6:7]
	s_cbranch_vccnz .LBB0_633
	s_barrier
	s_branch .LBB0_633
